# v39 + 12 compiler-duplicated s_waitcnt lgkmcnt(0) (directly behind the template wait) removed from the GEMM main loop and tail
# speedup vs baseline: 1.0089x; 1.0089x over previous
; #define LDA(dst, b, h) _Pragma("unroll") for (int m = 0; m < 4; ++m) _Pragma("unroll") for (int k = 0; k < 2; ++k) \
;     dst[m][k] = *reinterpret_cast<const bf16x8*>((char*)SA(b, h) + lds_byte(wr * 64 + m * 16 + fr, k * 32 + fq * 8))
; #define LDB(dst, b, h) _Pragma("unroll") for (int n = 0; n < 2; ++n) _Pragma("unroll") for (int k = 0; k < 2; ++k) \
;     dst[n][k] = *reinterpret_cast<const bf16x8*>((char*)SB(b, h) + lds_byte(wc * 32 + n * 16 + fr, k * 32 + fq * 8))
; #define MMA(ai, bj, At_, Bt_) do { __builtin_amdgcn_s_setprio(1); \
;     _Pragma("unroll") for (int m = 0; m < 4; ++m) _Pragma("unroll") for (int n = 0; n < 2; ++n) _Pragma("unroll") for (int k = 0; k < 2; ++k) \
;       acc[ai][bj][m][n] = __builtin_amdgcn_mfma_f32_16x16x32_bf16(Bt_[n][k], At_[m][k], acc[ai][bj][m][n], 0, 0, 0); \
;     __builtin_amdgcn_s_setprio(0); } while (0)
; #define WAIT_V(n) asm volatile("s_waitcnt vmcnt(" #n ")" ::: "memory")
; #define WAIT_L(n) asm volatile("s_waitcnt lgkmcnt(" #n ")" ::: "memory")
; #define BAR __builtin_amdgcn_s_barrier()
; #define SCHED __builtin_amdgcn_sched_barrier(0)
; __device__ __forceinline__ void gemm_tile(const TileDesc& td, unsigned char* lds) {
;     ...
;     for (int t = 0; t < nt - 2; t += 2) {
;         LDB(B0, 0, 0); SCHED; LDA(At, 0, 0); STAGE(SA(1, 1), A, lda, brow + HALF, t + 1);
;         WAIT_L(8); BAR; WAIT_L(0); MMA(0, 0, At, B0); BAR; SCHED;
;         LDB(B1, 0, 1); STAGE(SB(0, 0), Bt, ldb, bcol, t + 2);
;         BAR; WAIT_L(0); MMA(0, 1, At, B1); BAR;
;         LDA(At, 0, 1); STAGE(SA(0, 0), A, lda, brow, t + 2);
;         BAR; WAIT_L(0); MMA(1, 0, At, B0); BAR; SCHED;
;         STAGE(SB(0, 1), Bt, ldb, bcol + HALF, t + 2);
;         WAIT_V(6); BAR; MMA(1, 1, At, B1); BAR;
.LBB0_247:
	ds_read_b128 v[190:193], v183
	ds_read_b128 v[194:197], v183 offset:1024
	ds_read_b128 v[198:201], v183 offset:2048
	ds_read_b128 v[202:205], v183 offset:3072
	s_add_u32 s7, s4, s78
	s_addc_u32 s62, s5, s79
	s_add_u32 s30, s7, 0x80
	v_add_u32_e32 v162, 0xc000, v139
	s_addc_u32 s31, s62, 0
	v_readfirstlane_b32 s63, v162
	v_add_u32_e32 v252, v182, v154
	v_lshl_add_u64 v[160:161], s[30:31], 0, v[128:129]
	s_mov_b32 m0, s63
	v_add_u32_e32 v162, 0xe000, v139
	ds_read_b128 v[206:209], v252
	ds_read_b128 v[210:213], v252 offset:1024
	ds_read_b128 v[214:217], v184
	ds_read_b128 v[218:221], v184 offset:1024
	ds_read_b128 v[222:225], v185
	ds_read_b128 v[226:229], v185 offset:1024
	ds_read_b128 v[230:233], v186
	ds_read_b128 v[234:237], v186 offset:1024
	global_load_lds_dwordx4 v[160:161], off
	v_lshl_add_u64 v[160:161], s[30:31], 0, v[130:131]
	v_readfirstlane_b32 s30, v162
	s_mov_b32 m0, s30
	s_nop 0
	global_load_lds_dwordx4 v[160:161], off
	s_waitcnt lgkmcnt(8)
	s_barrier
	s_waitcnt lgkmcnt(0)
	v_mfma_f32_16x16x32_bf16 v[100:103], v[190:193], v[206:209], v[100:103]
	v_mfma_f32_16x16x32_bf16 v[124:127], v[198:201], v[206:209], v[124:127]
	v_mfma_f32_16x16x32_bf16 v[120:123], v[190:193], v[214:217], v[120:123]
	v_mfma_f32_16x16x32_bf16 v[116:119], v[198:201], v[214:217], v[116:119]
	v_mfma_f32_16x16x32_bf16 v[112:115], v[190:193], v[222:225], v[112:115]
	v_mfma_f32_16x16x32_bf16 v[108:111], v[198:201], v[222:225], v[108:111]
	v_mfma_f32_16x16x32_bf16 v[104:107], v[190:193], v[230:233], v[104:107]
	v_mfma_f32_16x16x32_bf16 v[96:99], v[198:201], v[230:233], v[96:99]
	v_mfma_f32_16x16x32_bf16 v[100:103], v[194:197], v[210:213], v[100:103]
	v_mfma_f32_16x16x32_bf16 v[124:127], v[202:205], v[210:213], v[124:127]
	v_mfma_f32_16x16x32_bf16 v[120:123], v[194:197], v[218:221], v[120:123]
	v_mfma_f32_16x16x32_bf16 v[116:119], v[202:205], v[218:221], v[116:119]
	v_mfma_f32_16x16x32_bf16 v[112:115], v[194:197], v[226:229], v[112:115]
	v_mfma_f32_16x16x32_bf16 v[108:111], v[202:205], v[226:229], v[108:111]
	v_mfma_f32_16x16x32_bf16 v[104:107], v[194:197], v[234:237], v[104:107]
	v_mfma_f32_16x16x32_bf16 v[96:99], v[202:205], v[234:237], v[96:99]
	s_barrier
	s_add_i32 s3, s3, 2
	s_add_u32 s63, s18, s78
	s_addc_u32 s65, s19, s79
	s_add_u32 s30, s63, 0x100
	s_addc_u32 s31, s65, 0
	v_readfirstlane_b32 s66, v152
	v_lshl_add_u64 v[168:169], s[30:31], 0, v[132:133]
	s_mov_b32 m0, s66
	ds_read_b128 v[238:241], v187
	ds_read_b128 v[242:245], v187 offset:1024
	ds_read_b128 v[246:249], v187 offset:2048
	ds_read_b128 v[160:163], v187 offset:3072
	global_load_lds_dwordx4 v[168:169], off
	v_lshl_add_u64 v[168:169], s[30:31], 0, v[136:137]
	v_readfirstlane_b32 s30, v153
	s_mov_b32 m0, s30
	s_nop 0
	global_load_lds_dwordx4 v[168:169], off
	s_barrier
	s_waitcnt lgkmcnt(0)
	v_mfma_f32_16x16x32_bf16 v[92:95], v[238:241], v[206:209], v[92:95]
	v_mfma_f32_16x16x32_bf16 v[88:91], v[246:249], v[206:209], v[88:91]
	v_mfma_f32_16x16x32_bf16 v[84:87], v[238:241], v[214:217], v[84:87]
	v_mfma_f32_16x16x32_bf16 v[80:83], v[246:249], v[214:217], v[80:83]
	v_mfma_f32_16x16x32_bf16 v[76:79], v[238:241], v[222:225], v[76:79]
	v_mfma_f32_16x16x32_bf16 v[72:75], v[246:249], v[222:225], v[72:75]
	v_mfma_f32_16x16x32_bf16 v[68:71], v[238:241], v[230:233], v[68:71]
	v_mfma_f32_16x16x32_bf16 v[64:67], v[246:249], v[230:233], v[64:67]
	v_mfma_f32_16x16x32_bf16 v[92:95], v[242:245], v[210:213], v[92:95]
	v_mfma_f32_16x16x32_bf16 v[88:91], v[160:163], v[210:213], v[88:91]
	v_mfma_f32_16x16x32_bf16 v[84:87], v[242:245], v[218:221], v[84:87]
	v_mfma_f32_16x16x32_bf16 v[80:83], v[160:163], v[218:221], v[80:83]
	v_mfma_f32_16x16x32_bf16 v[76:79], v[242:245], v[226:229], v[76:79]
	v_mfma_f32_16x16x32_bf16 v[72:75], v[160:163], v[226:229], v[72:75]
	v_mfma_f32_16x16x32_bf16 v[68:71], v[242:245], v[234:237], v[68:71]
	v_mfma_f32_16x16x32_bf16 v[64:67], v[160:163], v[234:237], v[64:67]
	s_add_u32 s66, s24, s78
	s_addc_u32 s67, s25, s79
	s_add_u32 s30, s66, 0x100
	s_addc_u32 s31, s67, 0
	v_readfirstlane_b32 s70, v139
	v_lshl_add_u64 v[168:169], s[30:31], 0, v[128:129]
	s_mov_b32 m0, s70
	s_barrier
	ds_read_b128 v[206:209], v252 offset:16384
	ds_read_b128 v[210:213], v252 offset:17408
	ds_read_b128 v[214:217], v184 offset:16384
	ds_read_b128 v[218:221], v184 offset:17408
	ds_read_b128 v[222:225], v185 offset:16384
	ds_read_b128 v[226:229], v185 offset:17408
	ds_read_b128 v[230:233], v186 offset:16384
	ds_read_b128 v[234:237], v186 offset:17408
	global_load_lds_dwordx4 v[168:169], off
	v_lshl_add_u64 v[168:169], s[30:31], 0, v[130:131]
	v_readfirstlane_b32 s30, v155
	s_mov_b32 m0, s30
	s_nop 0
	global_load_lds_dwordx4 v[168:169], off
	s_barrier
	s_waitcnt lgkmcnt(0)
	v_mfma_f32_16x16x32_bf16 v[60:63], v[190:193], v[206:209], v[60:63]
	v_mfma_f32_16x16x32_bf16 v[56:59], v[198:201], v[206:209], v[56:59]
	v_mfma_f32_16x16x32_bf16 v[52:55], v[190:193], v[214:217], v[52:55]
	v_mfma_f32_16x16x32_bf16 v[48:51], v[198:201], v[214:217], v[48:51]
	v_mfma_f32_16x16x32_bf16 v[44:47], v[190:193], v[222:225], v[44:47]
	v_mfma_f32_16x16x32_bf16 v[40:43], v[198:201], v[222:225], v[40:43]
	v_mfma_f32_16x16x32_bf16 v[36:39], v[190:193], v[230:233], v[36:39]
	v_mfma_f32_16x16x32_bf16 v[32:35], v[198:201], v[230:233], v[32:35]
	v_mfma_f32_16x16x32_bf16 v[60:63], v[194:197], v[210:213], v[60:63]
	v_mfma_f32_16x16x32_bf16 v[56:59], v[202:205], v[210:213], v[56:59]
	v_mfma_f32_16x16x32_bf16 v[52:55], v[194:197], v[218:221], v[52:55]
	v_mfma_f32_16x16x32_bf16 v[48:51], v[202:205], v[218:221], v[48:51]
	v_mfma_f32_16x16x32_bf16 v[44:47], v[194:197], v[226:229], v[44:47]
	v_mfma_f32_16x16x32_bf16 v[40:43], v[202:205], v[226:229], v[40:43]
	v_mfma_f32_16x16x32_bf16 v[36:39], v[194:197], v[234:237], v[36:39]
	v_mfma_f32_16x16x32_bf16 v[32:35], v[202:205], v[234:237], v[32:35]
	s_barrier
; #define LDA(dst, b, h) _Pragma("unroll") for (int m = 0; m < 4; ++m) _Pragma("unroll") for (int k = 0; k < 2; ++k) \
;     dst[m][k] = *reinterpret_cast<const bf16x8*>((char*)SA(b, h) + lds_byte(wr * 64 + m * 16 + fr, k * 32 + fq * 8))
; #define LDB(dst, b, h) _Pragma("unroll") for (int n = 0; n < 2; ++n) _Pragma("unroll") for (int k = 0; k < 2; ++k) \
;     dst[n][k] = *reinterpret_cast<const bf16x8*>((char*)SB(b, h) + lds_byte(wc * 32 + n * 16 + fr, k * 32 + fq * 8))
; #define MMA(ai, bj, At_, Bt_) do { __builtin_amdgcn_s_setprio(1); \
;     _Pragma("unroll") for (int m = 0; m < 4; ++m) _Pragma("unroll") for (int n = 0; n < 2; ++n) _Pragma("unroll") for (int k = 0; k < 2; ++k) \
;       acc[ai][bj][m][n] = __builtin_amdgcn_mfma_f32_16x16x32_bf16(Bt_[n][k], At_[m][k], acc[ai][bj][m][n], 0, 0, 0); \
;     __builtin_amdgcn_s_setprio(0); } while (0)
; #define WAIT_V(n) asm volatile("s_waitcnt vmcnt(" #n ")" ::: "memory")
; #define WAIT_L(n) asm volatile("s_waitcnt lgkmcnt(" #n ")" ::: "memory")
; #define BAR __builtin_amdgcn_s_barrier()
; #define SCHED __builtin_amdgcn_sched_barrier(0)
; __device__ __forceinline__ void gemm_tile(const TileDesc& td, unsigned char* lds) {
;     ...
;         STAGE(SB(0, 1), Bt, ldb, bcol + HALF, t + 2);
;         WAIT_V(6); BAR; MMA(1, 1, At, B1); BAR;
;         LDB(B0, 1, 0); SCHED; LDA(At, 1, 0); STAGE(SA(0, 1), A, lda, brow + HALF, t + 2);
;         WAIT_L(8); BAR; WAIT_L(0); MMA(0, 0, At, B0); BAR; SCHED;
;         LDB(B1, 1, 1); STAGE(SB(1, 0), Bt, ldb, bcol, t + 3);
;         BAR; WAIT_L(0); MMA(0, 1, At, B1); BAR;
;         LDA(At, 1, 1); STAGE(SA(1, 0), A, lda, brow, t + 3);
;         BAR; WAIT_L(0); MMA(1, 0, At, B0); BAR; SCHED;
;         STAGE(SB(1, 1), Bt, ldb, bcol + HALF, t + 3);
	s_add_u32 s70, s80, s78
	s_addc_u32 s88, s81, s79
	s_add_u32 s30, s70, 0x100
	s_addc_u32 s31, s88, 0
	v_readfirstlane_b32 s89, v156
	v_lshl_add_u64 v[168:169], s[30:31], 0, v[132:133]
	s_mov_b32 m0, s89
	s_nop 0
	global_load_lds_dwordx4 v[168:169], off
	v_lshl_add_u64 v[168:169], s[30:31], 0, v[136:137]
	v_readfirstlane_b32 s30, v157
	s_mov_b32 m0, s30
	s_nop 0
	global_load_lds_dwordx4 v[168:169], off
	s_waitcnt vmcnt(6)
	s_barrier
	v_mfma_f32_16x16x32_bf16 v[28:31], v[238:241], v[206:209], v[28:31]
	v_mfma_f32_16x16x32_bf16 v[24:27], v[246:249], v[206:209], v[24:27]
	v_mfma_f32_16x16x32_bf16 v[20:23], v[238:241], v[214:217], v[20:23]
	v_mfma_f32_16x16x32_bf16 v[16:19], v[246:249], v[214:217], v[16:19]
	v_mfma_f32_16x16x32_bf16 v[12:15], v[238:241], v[222:225], v[12:15]
	v_mfma_f32_16x16x32_bf16 v[8:11], v[246:249], v[222:225], v[8:11]
	v_mfma_f32_16x16x32_bf16 v[4:7], v[238:241], v[230:233], v[4:7]
	v_mfma_f32_16x16x32_bf16 v[0:3], v[246:249], v[230:233], v[0:3]
	v_mfma_f32_16x16x32_bf16 v[28:31], v[242:245], v[210:213], v[28:31]
	v_mfma_f32_16x16x32_bf16 v[24:27], v[160:163], v[210:213], v[24:27]
	v_mfma_f32_16x16x32_bf16 v[20:23], v[242:245], v[218:221], v[20:23]
	v_mfma_f32_16x16x32_bf16 v[16:19], v[160:163], v[218:221], v[16:19]
	v_mfma_f32_16x16x32_bf16 v[12:15], v[242:245], v[226:229], v[12:15]
	v_mfma_f32_16x16x32_bf16 v[8:11], v[160:163], v[226:229], v[8:11]
	v_mfma_f32_16x16x32_bf16 v[4:7], v[242:245], v[234:237], v[4:7]
	v_mfma_f32_16x16x32_bf16 v[0:3], v[160:163], v[234:237], v[0:3]
	s_barrier
	ds_read_b128 v[160:163], v188
	ds_read_b128 v[190:193], v188 offset:1024
	ds_read_b128 v[194:197], v188 offset:2048
	ds_read_b128 v[198:201], v188 offset:3072
	s_add_u32 s30, s7, 0x100
	s_addc_u32 s31, s62, 0
	v_readfirstlane_b32 s7, v174
	v_lshl_add_u64 v[168:169], s[30:31], 0, v[128:129]
	s_mov_b32 m0, s7
	v_readfirstlane_b32 s7, v175
	ds_read_b128 v[202:205], v252 offset:32768
	ds_read_b128 v[206:209], v252 offset:33792
	ds_read_b128 v[210:213], v184 offset:32768
	ds_read_b128 v[214:217], v184 offset:33792
	ds_read_b128 v[218:221], v185 offset:32768
	ds_read_b128 v[222:225], v185 offset:33792
	ds_read_b128 v[226:229], v186 offset:32768
	ds_read_b128 v[230:233], v186 offset:33792
	global_load_lds_dwordx4 v[168:169], off
	v_lshl_add_u64 v[168:169], s[30:31], 0, v[130:131]
	s_mov_b32 m0, s7
	s_nop 0
	global_load_lds_dwordx4 v[168:169], off
	s_waitcnt lgkmcnt(8)
	s_barrier
	s_waitcnt lgkmcnt(0)
	v_mfma_f32_16x16x32_bf16 v[100:103], v[160:163], v[202:205], v[100:103]
	v_mfma_f32_16x16x32_bf16 v[124:127], v[194:197], v[202:205], v[124:127]
	v_mfma_f32_16x16x32_bf16 v[120:123], v[160:163], v[210:213], v[120:123]
	v_mfma_f32_16x16x32_bf16 v[116:119], v[194:197], v[210:213], v[116:119]
	v_mfma_f32_16x16x32_bf16 v[112:115], v[160:163], v[218:221], v[112:115]
	v_mfma_f32_16x16x32_bf16 v[108:111], v[194:197], v[218:221], v[108:111]
	v_mfma_f32_16x16x32_bf16 v[104:107], v[160:163], v[226:229], v[104:107]
	v_mfma_f32_16x16x32_bf16 v[96:99], v[194:197], v[226:229], v[96:99]
	v_mfma_f32_16x16x32_bf16 v[100:103], v[190:193], v[206:209], v[100:103]
	v_mfma_f32_16x16x32_bf16 v[124:127], v[198:201], v[206:209], v[124:127]
	v_mfma_f32_16x16x32_bf16 v[120:123], v[190:193], v[214:217], v[120:123]
	v_mfma_f32_16x16x32_bf16 v[116:119], v[198:201], v[214:217], v[116:119]
	v_mfma_f32_16x16x32_bf16 v[112:115], v[190:193], v[222:225], v[112:115]
	v_mfma_f32_16x16x32_bf16 v[108:111], v[198:201], v[222:225], v[108:111]
	v_mfma_f32_16x16x32_bf16 v[104:107], v[190:193], v[230:233], v[104:107]
	v_mfma_f32_16x16x32_bf16 v[96:99], v[198:201], v[230:233], v[96:99]
	s_barrier
	s_add_u32 s30, s63, 0x180
	s_addc_u32 s31, s65, 0
	v_readfirstlane_b32 s7, v176
	v_lshl_add_u64 v[168:169], s[30:31], 0, v[132:133]
	s_mov_b32 m0, s7
	v_readfirstlane_b32 s7, v177
	ds_read_b128 v[234:237], v189
	ds_read_b128 v[238:241], v189 offset:1024
	ds_read_b128 v[242:245], v189 offset:2048
	ds_read_b128 v[246:249], v189 offset:3072
	global_load_lds_dwordx4 v[168:169], off
	v_lshl_add_u64 v[168:169], s[30:31], 0, v[136:137]
	s_mov_b32 m0, s7
	s_nop 0
	global_load_lds_dwordx4 v[168:169], off
	s_barrier
	s_waitcnt lgkmcnt(0)
	v_mfma_f32_16x16x32_bf16 v[92:95], v[234:237], v[202:205], v[92:95]
	v_mfma_f32_16x16x32_bf16 v[88:91], v[242:245], v[202:205], v[88:91]
	v_mfma_f32_16x16x32_bf16 v[84:87], v[234:237], v[210:213], v[84:87]
	v_mfma_f32_16x16x32_bf16 v[80:83], v[242:245], v[210:213], v[80:83]
	v_mfma_f32_16x16x32_bf16 v[76:79], v[234:237], v[218:221], v[76:79]
	v_mfma_f32_16x16x32_bf16 v[72:75], v[242:245], v[218:221], v[72:75]
	v_mfma_f32_16x16x32_bf16 v[68:71], v[234:237], v[226:229], v[68:71]
	v_mfma_f32_16x16x32_bf16 v[64:67], v[242:245], v[226:229], v[64:67]
	v_mfma_f32_16x16x32_bf16 v[92:95], v[238:241], v[206:209], v[92:95]
	v_mfma_f32_16x16x32_bf16 v[88:91], v[246:249], v[206:209], v[88:91]
	v_mfma_f32_16x16x32_bf16 v[84:87], v[238:241], v[214:217], v[84:87]
	v_mfma_f32_16x16x32_bf16 v[80:83], v[246:249], v[214:217], v[80:83]
	v_mfma_f32_16x16x32_bf16 v[76:79], v[238:241], v[222:225], v[76:79]
	v_mfma_f32_16x16x32_bf16 v[72:75], v[246:249], v[222:225], v[72:75]
	v_mfma_f32_16x16x32_bf16 v[68:71], v[238:241], v[230:233], v[68:71]
	v_mfma_f32_16x16x32_bf16 v[64:67], v[246:249], v[230:233], v[64:67]
	s_add_u32 s30, s66, 0x180
	s_addc_u32 s31, s67, 0
	v_readfirstlane_b32 s7, v178
	v_lshl_add_u64 v[168:169], s[30:31], 0, v[128:129]
	s_mov_b32 m0, s7
	v_readfirstlane_b32 s7, v179
	s_barrier
; #define LDA(dst, b, h) _Pragma("unroll") for (int m = 0; m < 4; ++m) _Pragma("unroll") for (int k = 0; k < 2; ++k) \
;     dst[m][k] = *reinterpret_cast<const bf16x8*>((char*)SA(b, h) + lds_byte(wr * 64 + m * 16 + fr, k * 32 + fq * 8))
; #define LDB(dst, b, h) _Pragma("unroll") for (int n = 0; n < 2; ++n) _Pragma("unroll") for (int k = 0; k < 2; ++k) \
;     dst[n][k] = *reinterpret_cast<const bf16x8*>((char*)SB(b, h) + lds_byte(wc * 32 + n * 16 + fr, k * 32 + fq * 8))
; #define MMA(ai, bj, At_, Bt_) do { __builtin_amdgcn_s_setprio(1); \
;     _Pragma("unroll") for (int m = 0; m < 4; ++m) _Pragma("unroll") for (int n = 0; n < 2; ++n) _Pragma("unroll") for (int k = 0; k < 2; ++k) \
;       acc[ai][bj][m][n] = __builtin_amdgcn_mfma_f32_16x16x32_bf16(Bt_[n][k], At_[m][k], acc[ai][bj][m][n], 0, 0, 0); \
;     __builtin_amdgcn_s_setprio(0); } while (0)
; #define WAIT_V(n) asm volatile("s_waitcnt vmcnt(" #n ")" ::: "memory")
; #define WAIT_L(n) asm volatile("s_waitcnt lgkmcnt(" #n ")" ::: "memory")
; #define BAR __builtin_amdgcn_s_barrier()
; #define SCHED __builtin_amdgcn_sched_barrier(0)
; __device__ __forceinline__ void gemm_tile(const TileDesc& td, unsigned char* lds) {
;     ...
;         LDA(At, 1, 1); STAGE(SA(1, 0), A, lda, brow, t + 3);
;         BAR; WAIT_L(0); MMA(1, 0, At, B0); BAR; SCHED;
;         STAGE(SB(1, 1), Bt, ldb, bcol + HALF, t + 3);
;         WAIT_V(6); BAR; MMA(1, 1, At, B1); BAR;
;     }
;     { LDB(B0, 0, 0); LDA(At, 0, 0); STAGE(SA(1, 1), A, lda, brow + HALF, nt - 1);
;       BAR; WAIT_L(0); MMA(0, 0, At, B0); BAR;
	ds_read_b128 v[202:205], v252 offset:49152
	ds_read_b128 v[206:209], v252 offset:50176
	ds_read_b128 v[210:213], v184 offset:49152
	ds_read_b128 v[214:217], v184 offset:50176
	ds_read_b128 v[218:221], v185 offset:49152
	ds_read_b128 v[222:225], v185 offset:50176
	ds_read_b128 v[226:229], v186 offset:49152
	ds_read_b128 v[230:233], v186 offset:50176
	global_load_lds_dwordx4 v[168:169], off
	v_lshl_add_u64 v[168:169], s[30:31], 0, v[130:131]
	s_mov_b32 m0, s7
	s_nop 0
	global_load_lds_dwordx4 v[168:169], off
	s_barrier
	s_waitcnt lgkmcnt(0)
	v_mfma_f32_16x16x32_bf16 v[60:63], v[160:163], v[202:205], v[60:63]
	v_mfma_f32_16x16x32_bf16 v[56:59], v[194:197], v[202:205], v[56:59]
	v_mfma_f32_16x16x32_bf16 v[52:55], v[160:163], v[210:213], v[52:55]
	v_mfma_f32_16x16x32_bf16 v[48:51], v[194:197], v[210:213], v[48:51]
	v_mfma_f32_16x16x32_bf16 v[44:47], v[160:163], v[218:221], v[44:47]
	v_mfma_f32_16x16x32_bf16 v[40:43], v[194:197], v[218:221], v[40:43]
	v_mfma_f32_16x16x32_bf16 v[36:39], v[160:163], v[226:229], v[36:39]
	v_mfma_f32_16x16x32_bf16 v[32:35], v[194:197], v[226:229], v[32:35]
	v_mfma_f32_16x16x32_bf16 v[60:63], v[190:193], v[206:209], v[60:63]
	v_mfma_f32_16x16x32_bf16 v[56:59], v[198:201], v[206:209], v[56:59]
	v_mfma_f32_16x16x32_bf16 v[52:55], v[190:193], v[214:217], v[52:55]
	v_mfma_f32_16x16x32_bf16 v[48:51], v[198:201], v[214:217], v[48:51]
	v_mfma_f32_16x16x32_bf16 v[44:47], v[190:193], v[222:225], v[44:47]
	v_mfma_f32_16x16x32_bf16 v[40:43], v[198:201], v[222:225], v[40:43]
	v_mfma_f32_16x16x32_bf16 v[36:39], v[190:193], v[230:233], v[36:39]
	v_mfma_f32_16x16x32_bf16 v[32:35], v[198:201], v[230:233], v[32:35]
	s_barrier
	s_add_u32 s30, s70, 0x180
	s_addc_u32 s31, s88, 0
	v_readfirstlane_b32 s7, v180
	v_lshl_add_u64 v[160:161], s[30:31], 0, v[132:133]
	s_mov_b32 m0, s7
	v_readfirstlane_b32 s7, v181
	global_load_lds_dwordx4 v[160:161], off
	v_lshl_add_u64 v[160:161], s[30:31], 0, v[136:137]
	s_mov_b32 m0, s7
	s_nop 0
	global_load_lds_dwordx4 v[160:161], off
	s_waitcnt vmcnt(6)
	s_barrier
	v_mfma_f32_16x16x32_bf16 v[28:31], v[234:237], v[202:205], v[28:31]
	v_mfma_f32_16x16x32_bf16 v[24:27], v[242:245], v[202:205], v[24:27]
	v_mfma_f32_16x16x32_bf16 v[20:23], v[234:237], v[210:213], v[20:23]
	v_mfma_f32_16x16x32_bf16 v[16:19], v[242:245], v[210:213], v[16:19]
	v_mfma_f32_16x16x32_bf16 v[12:15], v[234:237], v[218:221], v[12:15]
	v_mfma_f32_16x16x32_bf16 v[8:11], v[242:245], v[218:221], v[8:11]
	v_mfma_f32_16x16x32_bf16 v[4:7], v[234:237], v[226:229], v[4:7]
	v_mfma_f32_16x16x32_bf16 v[0:3], v[242:245], v[226:229], v[0:3]
	v_mfma_f32_16x16x32_bf16 v[28:31], v[238:241], v[206:209], v[28:31]
	v_mfma_f32_16x16x32_bf16 v[24:27], v[246:249], v[206:209], v[24:27]
	v_mfma_f32_16x16x32_bf16 v[20:23], v[238:241], v[214:217], v[20:23]
	v_mfma_f32_16x16x32_bf16 v[16:19], v[246:249], v[214:217], v[16:19]
	v_mfma_f32_16x16x32_bf16 v[12:15], v[238:241], v[222:225], v[12:15]
	v_mfma_f32_16x16x32_bf16 v[8:11], v[246:249], v[222:225], v[8:11]
	v_mfma_f32_16x16x32_bf16 v[4:7], v[238:241], v[230:233], v[4:7]
	v_mfma_f32_16x16x32_bf16 v[0:3], v[246:249], v[230:233], v[0:3]
	s_add_u32 s78, s78, 0x100
	s_addc_u32 s79, s79, 0
	s_cmp_lt_i32 s3, s2
	s_barrier
	s_cbranch_scc1 .LBB0_247
	v_or_b32_e32 v182, 0x400, v138
	v_or_b32_e32 v183, 0x800, v138
	v_or_b32_e32 v184, 0xc00, v138
	v_mov_b32_e32 v185, v154
	v_mov_b32_e32 v235, v159
	v_mov_b32_e32 v236, v172
	v_mov_b32_e32 v172, v170
	v_mov_b32_e32 v170, v173
	v_mov_b32_e32 v237, v165
	v_mov_b32_e32 v165, v167
	v_mov_b32_e32 v238, v135
	v_mov_b32_e32 v135, v171
	v_mov_b32_e32 v167, 0x42000000
.LBB0_249:
	v_add_u32_e32 v132, v151, v138
	v_add_u32_e32 v136, v151, v182
	ds_read_b128 v[152:155], v132
	ds_read_b128 v[160:163], v136
	v_add_u32_e32 v132, v151, v183
	v_add_u32_e32 v136, v151, v184
	s_ashr_i32 s7, s6, 31
	ds_read_b128 v[174:177], v132
	ds_read_b128 v[178:181], v136
	v_add_u32_e32 v136, 0, v142
	s_lshl_b64 s[2:3], s[6:7], 7
	v_add_u32_e32 v169, v136, v145
	v_add_u32_e32 v230, v136, v146
	v_add_u32_e32 v136, 0, v142
	s_add_u32 s2, s4, s2
	v_add_u32_e32 v231, v136, v147
	v_add_u32_e32 v232, v136, v148
	v_add_u32_e32 v136, 0, v142
	s_addc_u32 s3, s5, s3
	v_add_u32_e32 v233, v136, v149
	v_add_u32_e32 v234, v136, v150
	s_add_u32 s2, s2, 0xffffff80
	v_add_u32_e32 v136, 0xc000, v139
	v_add_u32_e32 v132, 0, v142
	s_addc_u32 s3, s3, -1
	v_readfirstlane_b32 s4, v136
	v_add_u32_e32 v168, v132, v185
	v_lshl_add_u64 v[128:129], s[2:3], 0, v[128:129]
	s_mov_b32 m0, s4
	v_add_u32_e32 v132, v132, v144
	ds_read_b128 v[186:189], v168
	ds_read_b128 v[190:193], v132
	ds_read_b128 v[194:197], v169
	ds_read_b128 v[198:201], v230
	ds_read_b128 v[144:147], v231
	ds_read_b128 v[202:205], v232
	ds_read_b128 v[148:151], v233
	ds_read_b128 v[206:209], v234
	global_load_lds_dwordx4 v[128:129], off
	v_lshl_add_u64 v[128:129], s[2:3], 0, v[130:131]
	v_add_u32_e32 v130, 0xe000, v139
	s_nop 0
	v_readfirstlane_b32 s2, v130
	s_mov_b32 m0, s2
	s_nop 0
	global_load_lds_dwordx4 v[128:129], off
	s_barrier
; #define LDA(dst, b, h) _Pragma("unroll") for (int m = 0; m < 4; ++m) _Pragma("unroll") for (int k = 0; k < 2; ++k) \
;     dst[m][k] = *reinterpret_cast<const bf16x8*>((char*)SA(b, h) + lds_byte(wr * 64 + m * 16 + fr, k * 32 + fq * 8))
; #define LDB(dst, b, h) _Pragma("unroll") for (int n = 0; n < 2; ++n) _Pragma("unroll") for (int k = 0; k < 2; ++k) \
;     dst[n][k] = *reinterpret_cast<const bf16x8*>((char*)SB(b, h) + lds_byte(wc * 32 + n * 16 + fr, k * 32 + fq * 8))
; #define MMA(ai, bj, At_, Bt_) do { __builtin_amdgcn_s_setprio(1); \
;     _Pragma("unroll") for (int m = 0; m < 4; ++m) _Pragma("unroll") for (int n = 0; n < 2; ++n) _Pragma("unroll") for (int k = 0; k < 2; ++k) \
;       acc[ai][bj][m][n] = __builtin_amdgcn_mfma_f32_16x16x32_bf16(Bt_[n][k], At_[m][k], acc[ai][bj][m][n], 0, 0, 0); \
;     __builtin_amdgcn_s_setprio(0); } while (0)
; #define WAIT_V(n) asm volatile("s_waitcnt vmcnt(" #n ")" ::: "memory")
; #define WAIT_L(n) asm volatile("s_waitcnt lgkmcnt(" #n ")" ::: "memory")
; #define BAR __builtin_amdgcn_s_barrier()
; __device__ __forceinline__ void gemm_tile(const TileDesc& td, unsigned char* lds) {
;     ...
;     { LDB(B0, 0, 0); LDA(At, 0, 0); STAGE(SA(1, 1), A, lda, brow + HALF, nt - 1);
;       BAR; WAIT_L(0); MMA(0, 0, At, B0); BAR;
;       LDB(B1, 0, 1); BAR; WAIT_L(0); MMA(0, 1, At, B1); BAR;
;       LDA(At, 0, 1); WAIT_V(4); BAR; WAIT_L(0); MMA(1, 0, At, B0); MMA(1, 1, At, B1); BAR; }
;     { LDB(B0, 1, 0); LDA(At, 1, 0); WAIT_V(2); BAR; WAIT_L(0); MMA(0, 0, At, B0); BAR;
	s_waitcnt lgkmcnt(0)
	v_mfma_f32_16x16x32_bf16 v[100:103], v[152:155], v[186:189], v[100:103]
	v_mfma_f32_16x16x32_bf16 v[96:99], v[174:177], v[148:151], v[96:99]
	v_mfma_f32_16x16x32_bf16 v[100:103], v[160:163], v[190:193], v[100:103]
	v_mfma_f32_16x16x32_bf16 v[124:127], v[174:177], v[186:189], v[124:127]
	v_mfma_f32_16x16x32_bf16 v[120:123], v[152:155], v[194:197], v[120:123]
	v_mfma_f32_16x16x32_bf16 v[116:119], v[174:177], v[194:197], v[116:119]
	v_mfma_f32_16x16x32_bf16 v[112:115], v[152:155], v[144:147], v[112:115]
	v_mfma_f32_16x16x32_bf16 v[108:111], v[174:177], v[144:147], v[108:111]
	v_mfma_f32_16x16x32_bf16 v[104:107], v[152:155], v[148:151], v[104:107]
	v_mfma_f32_16x16x32_bf16 v[96:99], v[178:181], v[206:209], v[96:99]
	v_mfma_f32_16x16x32_bf16 v[128:131], v[178:181], v[190:193], v[124:127]
	v_mfma_f32_16x16x32_bf16 v[210:213], v[160:163], v[198:201], v[120:123]
	v_mfma_f32_16x16x32_bf16 v[214:217], v[178:181], v[198:201], v[116:119]
	v_mfma_f32_16x16x32_bf16 v[218:221], v[160:163], v[202:205], v[112:115]
	v_mfma_f32_16x16x32_bf16 v[222:225], v[178:181], v[202:205], v[108:111]
	v_mfma_f32_16x16x32_bf16 v[226:229], v[160:163], v[206:209], v[104:107]
	s_nop 1
	v_add_u32_e32 v104, v143, v138
	v_add_u32_e32 v108, v143, v182
	v_add_u32_e32 v112, v143, v183
	v_add_u32_e32 v116, v143, v184
	s_barrier
	ds_read_b128 v[104:107], v104
	ds_read_b128 v[108:111], v108
	ds_read_b128 v[112:115], v112
	ds_read_b128 v[116:119], v116
	s_barrier
	s_waitcnt lgkmcnt(0)
	v_mfma_f32_16x16x32_bf16 v[92:95], v[104:107], v[186:189], v[92:95]
	v_mfma_f32_16x16x32_bf16 v[88:91], v[112:115], v[186:189], v[88:91]
	v_mfma_f32_16x16x32_bf16 v[84:87], v[104:107], v[194:197], v[84:87]
	v_mfma_f32_16x16x32_bf16 v[80:83], v[112:115], v[194:197], v[80:83]
	v_mfma_f32_16x16x32_bf16 v[76:79], v[104:107], v[144:147], v[76:79]
	v_mfma_f32_16x16x32_bf16 v[72:75], v[112:115], v[144:147], v[72:75]
	v_mfma_f32_16x16x32_bf16 v[68:71], v[104:107], v[148:151], v[68:71]
	v_mfma_f32_16x16x32_bf16 v[64:67], v[112:115], v[148:151], v[64:67]
	v_mfma_f32_16x16x32_bf16 v[92:95], v[108:111], v[190:193], v[92:95]
	v_mfma_f32_16x16x32_bf16 v[88:91], v[116:119], v[190:193], v[88:91]
	v_mfma_f32_16x16x32_bf16 v[84:87], v[108:111], v[198:201], v[84:87]
	v_mfma_f32_16x16x32_bf16 v[80:83], v[116:119], v[198:201], v[80:83]
	v_mfma_f32_16x16x32_bf16 v[76:79], v[108:111], v[202:205], v[76:79]
	v_mfma_f32_16x16x32_bf16 v[72:75], v[116:119], v[202:205], v[72:75]
	v_mfma_f32_16x16x32_bf16 v[68:71], v[108:111], v[206:209], v[68:71]
	v_mfma_f32_16x16x32_bf16 v[64:67], v[116:119], v[206:209], v[64:67]
	s_barrier
	ds_read_b128 v[120:123], v168 offset:16384
	ds_read_b128 v[124:127], v132 offset:16384
	ds_read_b128 v[142:145], v169 offset:16384
	ds_read_b128 v[146:149], v230 offset:16384
	ds_read_b128 v[186:189], v231 offset:16384
	ds_read_b128 v[190:193], v232 offset:16384
	ds_read_b128 v[194:197], v233 offset:16384
	ds_read_b128 v[198:201], v234 offset:16384
	s_waitcnt vmcnt(4)
	s_barrier
	s_waitcnt lgkmcnt(0)
	v_mfma_f32_16x16x32_bf16 v[60:63], v[152:155], v[120:123], v[60:63]
	v_mfma_f32_16x16x32_bf16 v[56:59], v[174:177], v[120:123], v[56:59]
	v_mfma_f32_16x16x32_bf16 v[52:55], v[152:155], v[142:145], v[52:55]
	v_mfma_f32_16x16x32_bf16 v[48:51], v[174:177], v[142:145], v[48:51]
	v_mfma_f32_16x16x32_bf16 v[44:47], v[152:155], v[186:189], v[44:47]
	v_mfma_f32_16x16x32_bf16 v[40:43], v[174:177], v[186:189], v[40:43]
	v_mfma_f32_16x16x32_bf16 v[36:39], v[152:155], v[194:197], v[36:39]
	v_mfma_f32_16x16x32_bf16 v[32:35], v[174:177], v[194:197], v[32:35]
	v_mfma_f32_16x16x32_bf16 v[60:63], v[160:163], v[124:127], v[60:63]
	v_mfma_f32_16x16x32_bf16 v[56:59], v[178:181], v[124:127], v[56:59]
	v_mfma_f32_16x16x32_bf16 v[52:55], v[160:163], v[146:149], v[52:55]
	v_mfma_f32_16x16x32_bf16 v[48:51], v[178:181], v[146:149], v[48:51]
	v_mfma_f32_16x16x32_bf16 v[44:47], v[160:163], v[190:193], v[44:47]
	v_mfma_f32_16x16x32_bf16 v[40:43], v[178:181], v[190:193], v[40:43]
	v_mfma_f32_16x16x32_bf16 v[36:39], v[160:163], v[198:201], v[36:39]
	v_mfma_f32_16x16x32_bf16 v[32:35], v[178:181], v[198:201], v[32:35]
	v_mfma_f32_16x16x32_bf16 v[28:31], v[104:107], v[120:123], v[28:31]
	v_mfma_f32_16x16x32_bf16 v[24:27], v[112:115], v[120:123], v[24:27]
	v_mfma_f32_16x16x32_bf16 v[20:23], v[104:107], v[142:145], v[20:23]
	v_mfma_f32_16x16x32_bf16 v[16:19], v[112:115], v[142:145], v[16:19]
	v_mfma_f32_16x16x32_bf16 v[12:15], v[104:107], v[186:189], v[12:15]
	v_mfma_f32_16x16x32_bf16 v[8:11], v[112:115], v[186:189], v[8:11]
	v_mfma_f32_16x16x32_bf16 v[4:7], v[104:107], v[194:197], v[4:7]
	v_mfma_f32_16x16x32_bf16 v[0:3], v[112:115], v[194:197], v[0:3]
	v_mfma_f32_16x16x32_bf16 v[28:31], v[108:111], v[124:127], v[28:31]
	v_mfma_f32_16x16x32_bf16 v[24:27], v[116:119], v[124:127], v[24:27]
	v_mfma_f32_16x16x32_bf16 v[20:23], v[108:111], v[146:149], v[20:23]
	v_mfma_f32_16x16x32_bf16 v[16:19], v[116:119], v[146:149], v[16:19]
	v_mfma_f32_16x16x32_bf16 v[12:15], v[108:111], v[190:193], v[12:15]
	v_mfma_f32_16x16x32_bf16 v[8:11], v[116:119], v[190:193], v[8:11]
	v_mfma_f32_16x16x32_bf16 v[4:7], v[108:111], v[198:201], v[4:7]
	v_mfma_f32_16x16x32_bf16 v[0:3], v[116:119], v[198:201], v[0:3]
	v_add_u32_e32 v104, v141, v138
	s_barrier
	v_add_u32_e32 v105, v141, v182
	ds_read_b128 v[142:145], v104
	ds_read_b128 v[146:149], v105
	v_add_u32_e32 v104, v141, v183
	v_add_u32_e32 v105, v141, v184
	ds_read_b128 v[150:153], v104
	ds_read_b128 v[154:157], v105
	ds_read_b128 v[160:163], v168 offset:32768
	ds_read_b128 v[174:177], v132 offset:32768
	ds_read_b128 v[178:181], v169 offset:32768
	ds_read_b128 v[186:189], v230 offset:32768
	ds_read_b128 v[190:193], v231 offset:32768
	ds_read_b128 v[194:197], v232 offset:32768
	ds_read_b128 v[198:201], v233 offset:32768
	ds_read_b128 v[202:205], v234 offset:32768
	s_waitcnt vmcnt(2)
	s_barrier
; #define LDA(dst, b, h) _Pragma("unroll") for (int m = 0; m < 4; ++m) _Pragma("unroll") for (int k = 0; k < 2; ++k) \
;     dst[m][k] = *reinterpret_cast<const bf16x8*>((char*)SA(b, h) + lds_byte(wr * 64 + m * 16 + fr, k * 32 + fq * 8))
; #define LDB(dst, b, h) _Pragma("unroll") for (int n = 0; n < 2; ++n) _Pragma("unroll") for (int k = 0; k < 2; ++k) \
;     dst[n][k] = *reinterpret_cast<const bf16x8*>((char*)SB(b, h) + lds_byte(wc * 32 + n * 16 + fr, k * 32 + fq * 8))
; #define MMA(ai, bj, At_, Bt_) do { __builtin_amdgcn_s_setprio(1); \
;     _Pragma("unroll") for (int m = 0; m < 4; ++m) _Pragma("unroll") for (int n = 0; n < 2; ++n) _Pragma("unroll") for (int k = 0; k < 2; ++k) \
;       acc[ai][bj][m][n] = __builtin_amdgcn_mfma_f32_16x16x32_bf16(Bt_[n][k], At_[m][k], acc[ai][bj][m][n], 0, 0, 0); \
;     __builtin_amdgcn_s_setprio(0); } while (0)
; #define WAIT_V(n) asm volatile("s_waitcnt vmcnt(" #n ")" ::: "memory")
; #define WAIT_L(n) asm volatile("s_waitcnt lgkmcnt(" #n ")" ::: "memory")
; #define BAR __builtin_amdgcn_s_barrier()
; __device__ __forceinline__ void gemm_tile(const TileDesc& td, unsigned char* lds) {
;     ...
;     { LDB(B0, 1, 0); LDA(At, 1, 0); WAIT_V(2); BAR; WAIT_L(0); MMA(0, 0, At, B0); BAR;
;       LDB(B1, 1, 1); WAIT_V(0); BAR; WAIT_L(0); MMA(0, 1, At, B1); BAR;
;       LDA(At, 1, 1); BAR; WAIT_L(0); MMA(1, 0, At, B0); MMA(1, 1, At, B1); BAR; }
;     if (wr == 0) BAR;
	s_waitcnt lgkmcnt(0)
	v_mfma_f32_16x16x32_bf16 v[100:103], v[142:145], v[160:163], v[100:103]
	v_mfma_f32_16x16x32_bf16 v[124:127], v[146:149], v[174:177], v[100:103]
	v_mfma_f32_16x16x32_bf16 v[100:103], v[150:153], v[160:163], v[128:131]
	v_mfma_f32_16x16x32_bf16 v[120:123], v[154:157], v[174:177], v[100:103]
	v_mfma_f32_16x16x32_bf16 v[100:103], v[142:145], v[178:181], v[210:213]
	v_mfma_f32_16x16x32_bf16 v[116:119], v[146:149], v[186:189], v[100:103]
	v_mfma_f32_16x16x32_bf16 v[100:103], v[150:153], v[178:181], v[214:217]
	v_mfma_f32_16x16x32_bf16 v[112:115], v[154:157], v[186:189], v[100:103]
	v_mfma_f32_16x16x32_bf16 v[100:103], v[142:145], v[190:193], v[218:221]
	v_mfma_f32_16x16x32_bf16 v[108:111], v[146:149], v[194:197], v[100:103]
	v_mfma_f32_16x16x32_bf16 v[100:103], v[150:153], v[190:193], v[222:225]
	v_mfma_f32_16x16x32_bf16 v[104:107], v[154:157], v[194:197], v[100:103]
	v_mfma_f32_16x16x32_bf16 v[100:103], v[142:145], v[198:201], v[226:229]
	v_mfma_f32_16x16x32_bf16 v[96:99], v[150:153], v[198:201], v[96:99]
	v_mfma_f32_16x16x32_bf16 v[100:103], v[146:149], v[202:205], v[100:103]
	v_mfma_f32_16x16x32_bf16 v[96:99], v[154:157], v[202:205], v[96:99]
	v_add_u32_e32 v128, v140, v138
	v_add_u32_e32 v136, v140, v182
	v_add_u32_e32 v141, v140, v183
	s_barrier
	ds_read_b128 v[128:131], v128
	ds_read_b128 v[136:139], v136
	v_add_u32_e32 v140, v140, v184
	ds_read_b128 v[182:185], v141
	ds_read_b128 v[206:209], v140
	s_waitcnt vmcnt(0)
	s_barrier
	s_waitcnt lgkmcnt(0)
	v_mfma_f32_16x16x32_bf16 v[92:95], v[128:131], v[160:163], v[92:95]
	v_mfma_f32_16x16x32_bf16 v[88:91], v[182:185], v[160:163], v[88:91]
	v_mfma_f32_16x16x32_bf16 v[84:87], v[128:131], v[178:181], v[84:87]
	v_mfma_f32_16x16x32_bf16 v[80:83], v[182:185], v[178:181], v[80:83]
	v_mfma_f32_16x16x32_bf16 v[76:79], v[128:131], v[190:193], v[76:79]
	v_mfma_f32_16x16x32_bf16 v[72:75], v[182:185], v[190:193], v[72:75]
	v_mfma_f32_16x16x32_bf16 v[68:71], v[128:131], v[198:201], v[68:71]
	v_mfma_f32_16x16x32_bf16 v[64:67], v[182:185], v[198:201], v[64:67]
	v_mfma_f32_16x16x32_bf16 v[92:95], v[136:139], v[174:177], v[92:95]
	v_mfma_f32_16x16x32_bf16 v[88:91], v[206:209], v[174:177], v[88:91]
	v_mfma_f32_16x16x32_bf16 v[84:87], v[136:139], v[186:189], v[84:87]
	v_mfma_f32_16x16x32_bf16 v[80:83], v[206:209], v[186:189], v[80:83]
	v_mfma_f32_16x16x32_bf16 v[76:79], v[136:139], v[194:197], v[76:79]
	v_mfma_f32_16x16x32_bf16 v[72:75], v[206:209], v[194:197], v[72:75]
	v_mfma_f32_16x16x32_bf16 v[68:71], v[136:139], v[202:205], v[68:71]
	v_mfma_f32_16x16x32_bf16 v[64:67], v[206:209], v[202:205], v[64:67]
	s_barrier
	ds_read_b128 v[160:163], v168 offset:49152
	ds_read_b128 v[174:177], v132 offset:49152
	ds_read_b128 v[178:181], v169 offset:49152
	ds_read_b128 v[186:189], v230 offset:49152
	ds_read_b128 v[190:193], v231 offset:49152
	ds_read_b128 v[194:197], v232 offset:49152
	ds_read_b128 v[198:201], v233 offset:49152
	ds_read_b128 v[202:205], v234 offset:49152
	s_barrier
	s_waitcnt lgkmcnt(0)
	v_mfma_f32_16x16x32_bf16 v[60:63], v[142:145], v[160:163], v[60:63]
	v_mfma_f32_16x16x32_bf16 v[56:59], v[150:153], v[160:163], v[56:59]
	v_mfma_f32_16x16x32_bf16 v[52:55], v[142:145], v[178:181], v[52:55]
	v_mfma_f32_16x16x32_bf16 v[48:51], v[150:153], v[178:181], v[48:51]
	v_mfma_f32_16x16x32_bf16 v[44:47], v[142:145], v[190:193], v[44:47]
	v_mfma_f32_16x16x32_bf16 v[40:43], v[150:153], v[190:193], v[40:43]
	v_mfma_f32_16x16x32_bf16 v[36:39], v[142:145], v[198:201], v[36:39]
	v_mfma_f32_16x16x32_bf16 v[32:35], v[150:153], v[198:201], v[32:35]
	v_mfma_f32_16x16x32_bf16 v[60:63], v[146:149], v[174:177], v[60:63]
	v_mfma_f32_16x16x32_bf16 v[56:59], v[154:157], v[174:177], v[56:59]
	v_mfma_f32_16x16x32_bf16 v[52:55], v[146:149], v[186:189], v[52:55]
	v_mfma_f32_16x16x32_bf16 v[48:51], v[154:157], v[186:189], v[48:51]
	v_mfma_f32_16x16x32_bf16 v[44:47], v[146:149], v[194:197], v[44:47]
	v_mfma_f32_16x16x32_bf16 v[40:43], v[154:157], v[194:197], v[40:43]
	v_mfma_f32_16x16x32_bf16 v[36:39], v[146:149], v[202:205], v[36:39]
	v_mfma_f32_16x16x32_bf16 v[32:35], v[154:157], v[202:205], v[32:35]
	v_mfma_f32_16x16x32_bf16 v[28:31], v[128:131], v[160:163], v[28:31]
	v_mfma_f32_16x16x32_bf16 v[24:27], v[182:185], v[160:163], v[24:27]
	v_mfma_f32_16x16x32_bf16 v[20:23], v[128:131], v[178:181], v[20:23]
	v_mfma_f32_16x16x32_bf16 v[16:19], v[182:185], v[178:181], v[16:19]
	v_mfma_f32_16x16x32_bf16 v[12:15], v[128:131], v[190:193], v[12:15]
	v_mfma_f32_16x16x32_bf16 v[8:11], v[182:185], v[190:193], v[8:11]
	v_mfma_f32_16x16x32_bf16 v[4:7], v[128:131], v[198:201], v[4:7]
	v_mfma_f32_16x16x32_bf16 v[0:3], v[182:185], v[198:201], v[0:3]
	v_mfma_f32_16x16x32_bf16 v[28:31], v[136:139], v[174:177], v[28:31]
	v_mfma_f32_16x16x32_bf16 v[24:27], v[206:209], v[174:177], v[24:27]
	v_mfma_f32_16x16x32_bf16 v[20:23], v[136:139], v[186:189], v[20:23]
	v_mfma_f32_16x16x32_bf16 v[16:19], v[206:209], v[186:189], v[16:19]
	v_mfma_f32_16x16x32_bf16 v[12:15], v[136:139], v[194:197], v[12:15]
	v_mfma_f32_16x16x32_bf16 v[8:11], v[206:209], v[194:197], v[8:11]
	v_mfma_f32_16x16x32_bf16 v[4:7], v[136:139], v[202:205], v[4:7]
	v_mfma_f32_16x16x32_bf16 v[0:3], v[206:209], v[202:205], v[0:3]
	s_movk_i32 s2, 0x100
	v_cmp_gt_u32_e32 vcc, s2, v134
	s_barrier
	s_and_saveexec_b64 s[4:5], vcc
	s_cbranch_execz .LBB0_251
	s_barrier
